# GEMM2 partial images in 16-byte pieces (two accumulator quads per write-through store / per combine load) instead of 8-byte ones
# speedup vs baseline: 1.0072x; 1.0072x over previous
.LBB0_613:
	s_and_b64 vcc, exec, s[0:1]
	s_cbranch_vccz .LBB0_630
	s_add_i32 s0, s15, s24
	s_ashr_i32 s1, s0, 31
	s_lshl_b64 s[0:1], s[0:1], 17
	s_add_u32 s0, s22, s0
	s_addc_u32 s1, s23, s1
	v_readlane_b32 s24, v254, 24
	s_add_u32 s24, s0, 0x823e000
	v_readlane_b32 s25, v254, 25
	v_readlane_b32 s26, v254, 26
	v_readlane_b32 s27, v254, 27
	s_addc_u32 s0, s1, 0
	s_and_b32 s25, s0, 0xffff
	s_mov_b32 s27, s26
	v_lshlrev_b32_e32 v4, 4, v249
	v_cvt_pk_bf16_f32 v138, v126, v127
	v_cvt_pk_bf16_f32 v139, v128, v129
	v_cvt_pk_bf16_f32 v140, v122, v123
	v_cvt_pk_bf16_f32 v141, v124, v125
	buffer_store_dwordx4 v[138:141], v4, s[24:27], 0 offen sc1
	v_cvt_pk_bf16_f32 v142, v114, v115
	v_cvt_pk_bf16_f32 v143, v116, v117
	v_cvt_pk_bf16_f32 v144, v106, v107
	v_cvt_pk_bf16_f32 v145, v108, v109
	s_mov_b32 s0, 0x2000
	buffer_store_dwordx4 v[142:145], v4, s[24:27], s0 offen sc1
	v_cvt_pk_bf16_f32 v138, v98, v99
	v_cvt_pk_bf16_f32 v139, v100, v101
	v_cvt_pk_bf16_f32 v140, v90, v91
	v_cvt_pk_bf16_f32 v141, v92, v93
	s_mov_b32 s0, 0x4000
	buffer_store_dwordx4 v[138:141], v4, s[24:27], s0 offen sc1
	v_cvt_pk_bf16_f32 v142, v82, v83
	v_cvt_pk_bf16_f32 v143, v84, v85
	v_cvt_pk_bf16_f32 v144, v74, v75
	v_cvt_pk_bf16_f32 v145, v76, v77
	s_mov_b32 s0, 0x6000
	buffer_store_dwordx4 v[142:145], v4, s[24:27], s0 offen sc1
	v_cvt_pk_bf16_f32 v138, v118, v119
	v_cvt_pk_bf16_f32 v139, v120, v121
	v_cvt_pk_bf16_f32 v140, v110, v111
	v_cvt_pk_bf16_f32 v141, v112, v113
	s_mov_b32 s0, 0x8000
	buffer_store_dwordx4 v[138:141], v4, s[24:27], s0 offen sc1
	v_cvt_pk_bf16_f32 v142, v102, v103
	v_cvt_pk_bf16_f32 v143, v104, v105
	v_cvt_pk_bf16_f32 v144, v94, v95
	v_cvt_pk_bf16_f32 v145, v96, v97
	s_mov_b32 s0, 0xa000
	buffer_store_dwordx4 v[142:145], v4, s[24:27], s0 offen sc1
	v_cvt_pk_bf16_f32 v138, v86, v87
	v_cvt_pk_bf16_f32 v139, v88, v89
	v_cvt_pk_bf16_f32 v140, v78, v79
	v_cvt_pk_bf16_f32 v141, v80, v81
	s_mov_b32 s0, 0xc000
	buffer_store_dwordx4 v[138:141], v4, s[24:27], s0 offen sc1
	v_cvt_pk_bf16_f32 v142, v70, v71
	v_cvt_pk_bf16_f32 v143, v72, v73
	v_cvt_pk_bf16_f32 v144, v66, v67
	v_cvt_pk_bf16_f32 v145, v68, v69
	s_mov_b32 s0, 0xe000
	buffer_store_dwordx4 v[142:145], v4, s[24:27], s0 offen sc1
	v_cvt_pk_bf16_f32 v138, v62, v63
	v_cvt_pk_bf16_f32 v139, v64, v65
	v_cvt_pk_bf16_f32 v140, v58, v59
	v_cvt_pk_bf16_f32 v141, v60, v61
	s_mov_b32 s0, 0x10000
	buffer_store_dwordx4 v[138:141], v4, s[24:27], s0 offen sc1
	v_cvt_pk_bf16_f32 v142, v50, v51
	v_cvt_pk_bf16_f32 v143, v52, v53
	v_cvt_pk_bf16_f32 v144, v42, v43
	v_cvt_pk_bf16_f32 v145, v44, v45
	s_mov_b32 s0, 0x12000
	buffer_store_dwordx4 v[142:145], v4, s[24:27], s0 offen sc1
	v_cvt_pk_bf16_f32 v138, v34, v35
	v_cvt_pk_bf16_f32 v139, v36, v37
	v_cvt_pk_bf16_f32 v140, v26, v27
	v_cvt_pk_bf16_f32 v141, v28, v29
	s_mov_b32 s0, 0x14000
	buffer_store_dwordx4 v[138:141], v4, s[24:27], s0 offen sc1
	v_cvt_pk_bf16_f32 v142, v18, v19
	v_cvt_pk_bf16_f32 v143, v20, v21
	v_cvt_pk_bf16_f32 v144, v136, v137
	v_cvt_pk_bf16_f32 v145, v134, v135
	s_mov_b32 s0, 0x16000
	buffer_store_dwordx4 v[142:145], v4, s[24:27], s0 offen sc1
	v_cvt_pk_bf16_f32 v138, v54, v55
	v_cvt_pk_bf16_f32 v139, v56, v57
	v_cvt_pk_bf16_f32 v140, v46, v47
	v_cvt_pk_bf16_f32 v141, v48, v49
	s_mov_b32 s0, 0x18000
	buffer_store_dwordx4 v[138:141], v4, s[24:27], s0 offen sc1
	v_cvt_pk_bf16_f32 v142, v38, v39
	v_cvt_pk_bf16_f32 v143, v40, v41
	v_cvt_pk_bf16_f32 v144, v30, v31
	v_cvt_pk_bf16_f32 v145, v32, v33
	s_mov_b32 s0, 0x1a000
	buffer_store_dwordx4 v[142:145], v4, s[24:27], s0 offen sc1
	v_cvt_pk_bf16_f32 v138, v22, v23
	v_cvt_pk_bf16_f32 v139, v24, v25
	v_cvt_pk_bf16_f32 v140, v14, v15
	v_cvt_pk_bf16_f32 v141, v16, v17
	s_mov_b32 s0, 0x1c000
	buffer_store_dwordx4 v[138:141], v4, s[24:27], s0 offen sc1
	v_cvt_pk_bf16_f32 v142, v6, v7
	v_cvt_pk_bf16_f32 v143, v8, v9
	v_cvt_pk_bf16_f32 v144, v12, v13
	v_cvt_pk_bf16_f32 v145, v10, v11
	s_mov_b32 s0, 0x1e000
	buffer_store_dwordx4 v[142:145], v4, s[24:27], s0 offen sc1
	s_mov_b32 s22, s26
	v_writelane_b32 v254, s20, 24
	s_waitcnt vmcnt(0)
	s_barrier
	v_writelane_b32 v254, s21, 25
	v_writelane_b32 v254, s22, 26
	v_writelane_b32 v254, s23, 27
	s_and_saveexec_b64 s[0:1], s[4:5]
	s_cbranch_execz .LBB0_616
	s_waitcnt vmcnt(0) lgkmcnt(0)
	s_waitcnt vmcnt(0)
	v_mov_b64_e32 v[2:3], s[20:21]
	flat_atomic_add v[2:3], v237 offset:4

.LBB0_629:
	s_or_b64 exec, exec, s[0:1]
	s_lshl_b64 s[0:1], s[24:25], 17
	s_add_u32 s0, s22, s0
	s_addc_u32 s1, s23, s1
	v_readlane_b32 s36, v254, 28
	s_add_u32 s36, s0, 0x823e000
	v_readlane_b32 s37, v254, 29
	s_addc_u32 s0, s1, 0
	s_barrier
	s_and_b32 s37, s0, 0xffff
	s_mov_b32 s1, s71
	s_mov_b32 s0, 0
	v_readlane_b32 s28, v254, 24
	s_xor_b64 s[0:1], s[0:1], s[62:63]
	v_ashrrev_i32_e32 v229, 31, v228
	v_readlane_b32 s39, v254, 31
	v_readlane_b32 s30, v254, 26
	s_add_u32 s26, s0, 0x723e000
	v_readlane_b32 s38, v254, 30
	s_mov_b32 s39, s30
	v_lshlrev_b32_e32 v132, 4, v249
	s_addc_u32 s27, s1, 0
	v_lshlrev_b64 v[2:3], 11, v[228:229]
	v_lshl_add_u64 v[130:131], s[26:27], 0, v[2:3]
	v_readlane_b32 s29, v254, 25
	v_readlane_b32 s31, v254, 27
	v_lshlrev_b32_e32 v131, 11, v228
	v_add_u32_e32 v131, v131, v212
	buffer_load_dwordx4 v[138:141], v132, s[36:39], 0 offen
	s_mov_b32 s0, 0x20000
	buffer_load_dwordx4 v[142:145], v132, s[36:39], s0 offen
	s_mov_b32 s0, 0x8000
	buffer_load_dwordx4 v[146:149], v132, s[36:39], s0 offen
	s_mov_b32 s0, 0x28000
	buffer_load_dwordx4 v[150:153], v132, s[36:39], s0 offen
	s_mov_b32 s0, 0x2000
	buffer_load_dwordx4 v[154:157], v132, s[36:39], s0 offen
	s_mov_b32 s0, 0x22000
	buffer_load_dwordx4 v[158:161], v132, s[36:39], s0 offen
	s_mov_b32 s0, 0xa000
	buffer_load_dwordx4 v[162:165], v132, s[36:39], s0 offen
	s_mov_b32 s0, 0x2a000
	buffer_load_dwordx4 v[166:169], v132, s[36:39], s0 offen
	s_mov_b32 s0, 0x4000
	buffer_load_dwordx4 v[170:173], v132, s[36:39], s0 offen
	s_mov_b32 s0, 0x24000
	buffer_load_dwordx4 v[174:177], v132, s[36:39], s0 offen
	s_mov_b32 s0, 0xc000
	buffer_load_dwordx4 v[178:181], v132, s[36:39], s0 offen
	s_mov_b32 s0, 0x2c000
	buffer_load_dwordx4 v[182:185], v132, s[36:39], s0 offen
	s_mov_b32 s0, 0x6000
	buffer_load_dwordx4 v[186:189], v132, s[36:39], s0 offen
	s_mov_b32 s0, 0x26000
	buffer_load_dwordx4 v[190:193], v132, s[36:39], s0 offen
	s_waitcnt vmcnt(12)
	v_lshlrev_b32_e32 v2, 16, v138
	v_and_b32_e32 v3, 0xffff0000, v138
	v_lshlrev_b32_e32 v4, 16, v139
	v_and_b32_e32 v5, 0xffff0000, v139
	v_pk_add_f32 v[126:127], v[126:127], v[2:3]
	v_pk_add_f32 v[128:129], v[128:129], v[4:5]
	v_lshlrev_b32_e32 v2, 16, v142
	v_and_b32_e32 v3, 0xffff0000, v142
	v_lshlrev_b32_e32 v4, 16, v143
	v_and_b32_e32 v5, 0xffff0000, v143
	v_pk_add_f32 v[126:127], v[126:127], v[2:3]
	v_pk_add_f32 v[128:129], v[128:129], v[4:5]
	v_lshlrev_b32_e32 v2, 16, v140
	v_and_b32_e32 v3, 0xffff0000, v140
	v_lshlrev_b32_e32 v4, 16, v141
	v_and_b32_e32 v5, 0xffff0000, v141
	v_pk_add_f32 v[122:123], v[122:123], v[2:3]
	v_pk_add_f32 v[124:125], v[124:125], v[4:5]
	v_lshlrev_b32_e32 v2, 16, v144
	v_and_b32_e32 v3, 0xffff0000, v144
	v_lshlrev_b32_e32 v4, 16, v145
	v_and_b32_e32 v5, 0xffff0000, v145
	v_pk_add_f32 v[122:123], v[122:123], v[2:3]
	v_pk_add_f32 v[124:125], v[124:125], v[4:5]
	v_cvt_pk_bf16_f32 v2, v126, v127
	v_cvt_pk_bf16_f32 v3, v128, v129
	v_cvt_pk_bf16_f32 v4, v122, v123
	v_cvt_pk_bf16_f32 v5, v124, v125
	global_store_dwordx4 v131, v[2:5], s[26:27]
	s_nop 1
	s_mov_b32 s0, 0xe000
	buffer_load_dwordx4 v[138:141], v132, s[36:39], s0 offen
	s_mov_b32 s0, 0x2e000
	buffer_load_dwordx4 v[142:145], v132, s[36:39], s0 offen
	s_waitcnt vmcnt(13)
	v_lshlrev_b32_e32 v2, 16, v146
	v_and_b32_e32 v3, 0xffff0000, v146
	v_lshlrev_b32_e32 v4, 16, v147
	v_and_b32_e32 v5, 0xffff0000, v147
	v_pk_add_f32 v[118:119], v[118:119], v[2:3]
	v_pk_add_f32 v[120:121], v[120:121], v[4:5]
	v_lshlrev_b32_e32 v2, 16, v150
	v_and_b32_e32 v3, 0xffff0000, v150
	v_lshlrev_b32_e32 v4, 16, v151
	v_and_b32_e32 v5, 0xffff0000, v151
	v_pk_add_f32 v[118:119], v[118:119], v[2:3]
	v_pk_add_f32 v[120:121], v[120:121], v[4:5]
	v_lshlrev_b32_e32 v2, 16, v148
	v_and_b32_e32 v3, 0xffff0000, v148
	v_lshlrev_b32_e32 v4, 16, v149
	v_and_b32_e32 v5, 0xffff0000, v149
	v_pk_add_f32 v[110:111], v[110:111], v[2:3]
	v_pk_add_f32 v[112:113], v[112:113], v[4:5]
	v_lshlrev_b32_e32 v2, 16, v152
	v_and_b32_e32 v3, 0xffff0000, v152
	v_lshlrev_b32_e32 v4, 16, v153
	v_and_b32_e32 v5, 0xffff0000, v153
	v_pk_add_f32 v[110:111], v[110:111], v[2:3]
	v_pk_add_f32 v[112:113], v[112:113], v[4:5]
	v_cvt_pk_bf16_f32 v2, v118, v119
	v_cvt_pk_bf16_f32 v3, v120, v121
	v_cvt_pk_bf16_f32 v4, v110, v111
	v_cvt_pk_bf16_f32 v5, v112, v113
	global_store_dwordx4 v131, v[2:5], s[26:27] offset:256
	s_nop 1
	s_mov_b32 s0, 0x10000
	buffer_load_dwordx4 v[146:149], v132, s[36:39], s0 offen
	s_mov_b32 s0, 0x30000
	buffer_load_dwordx4 v[150:153], v132, s[36:39], s0 offen
	s_waitcnt vmcnt(14)
	v_lshlrev_b32_e32 v2, 16, v154
	v_and_b32_e32 v3, 0xffff0000, v154
	v_lshlrev_b32_e32 v4, 16, v155
	v_and_b32_e32 v5, 0xffff0000, v155
	v_pk_add_f32 v[114:115], v[114:115], v[2:3]
	v_pk_add_f32 v[116:117], v[116:117], v[4:5]
	v_lshlrev_b32_e32 v2, 16, v158
	v_and_b32_e32 v3, 0xffff0000, v158
	v_lshlrev_b32_e32 v4, 16, v159
	v_and_b32_e32 v5, 0xffff0000, v159
	v_pk_add_f32 v[114:115], v[114:115], v[2:3]
	v_pk_add_f32 v[116:117], v[116:117], v[4:5]
	v_lshlrev_b32_e32 v2, 16, v156
	v_and_b32_e32 v3, 0xffff0000, v156
	v_lshlrev_b32_e32 v4, 16, v157
	v_and_b32_e32 v5, 0xffff0000, v157
	v_pk_add_f32 v[106:107], v[106:107], v[2:3]
	v_pk_add_f32 v[108:109], v[108:109], v[4:5]
	v_lshlrev_b32_e32 v2, 16, v160
	v_and_b32_e32 v3, 0xffff0000, v160
	v_lshlrev_b32_e32 v4, 16, v161
	v_and_b32_e32 v5, 0xffff0000, v161
	v_pk_add_f32 v[106:107], v[106:107], v[2:3]
	v_pk_add_f32 v[108:109], v[108:109], v[4:5]
	v_cvt_pk_bf16_f32 v2, v114, v115
	v_cvt_pk_bf16_f32 v3, v116, v117
	v_cvt_pk_bf16_f32 v4, v106, v107
	v_cvt_pk_bf16_f32 v5, v108, v109
	v_add_u32_e32 v130, 0x8000, v131
	global_store_dwordx4 v130, v[2:5], s[26:27]
	s_nop 1
	s_mov_b32 s0, 0x18000
	buffer_load_dwordx4 v[154:157], v132, s[36:39], s0 offen
	s_mov_b32 s0, 0x38000
	buffer_load_dwordx4 v[158:161], v132, s[36:39], s0 offen
	s_waitcnt vmcnt(15)
	v_lshlrev_b32_e32 v2, 16, v162
	v_and_b32_e32 v3, 0xffff0000, v162
	v_lshlrev_b32_e32 v4, 16, v163
	v_and_b32_e32 v5, 0xffff0000, v163
	v_pk_add_f32 v[102:103], v[102:103], v[2:3]
	v_pk_add_f32 v[104:105], v[104:105], v[4:5]
	v_lshlrev_b32_e32 v2, 16, v166
	v_and_b32_e32 v3, 0xffff0000, v166
	v_lshlrev_b32_e32 v4, 16, v167
	v_and_b32_e32 v5, 0xffff0000, v167
	v_pk_add_f32 v[102:103], v[102:103], v[2:3]
	v_pk_add_f32 v[104:105], v[104:105], v[4:5]
	v_lshlrev_b32_e32 v2, 16, v164
	v_and_b32_e32 v3, 0xffff0000, v164
	v_lshlrev_b32_e32 v4, 16, v165
	v_and_b32_e32 v5, 0xffff0000, v165
	v_pk_add_f32 v[94:95], v[94:95], v[2:3]
	v_pk_add_f32 v[96:97], v[96:97], v[4:5]
	v_lshlrev_b32_e32 v2, 16, v168
	v_and_b32_e32 v3, 0xffff0000, v168
	v_lshlrev_b32_e32 v4, 16, v169
	v_and_b32_e32 v5, 0xffff0000, v169
	v_pk_add_f32 v[94:95], v[94:95], v[2:3]
	v_pk_add_f32 v[96:97], v[96:97], v[4:5]
	v_cvt_pk_bf16_f32 v2, v102, v103
	v_cvt_pk_bf16_f32 v3, v104, v105
	v_cvt_pk_bf16_f32 v4, v94, v95
	v_cvt_pk_bf16_f32 v5, v96, v97
	v_add_u32_e32 v130, 0x8000, v131
	global_store_dwordx4 v130, v[2:5], s[26:27] offset:256
	s_nop 1
	s_mov_b32 s0, 0x12000
	buffer_load_dwordx4 v[162:165], v132, s[36:39], s0 offen
	s_mov_b32 s0, 0x32000
	buffer_load_dwordx4 v[166:169], v132, s[36:39], s0 offen
	s_waitcnt vmcnt(16)
	v_lshlrev_b32_e32 v2, 16, v170
	v_and_b32_e32 v3, 0xffff0000, v170
	v_lshlrev_b32_e32 v4, 16, v171
	v_and_b32_e32 v5, 0xffff0000, v171
	v_pk_add_f32 v[98:99], v[98:99], v[2:3]
	v_pk_add_f32 v[100:101], v[100:101], v[4:5]
	v_lshlrev_b32_e32 v2, 16, v174
	v_and_b32_e32 v3, 0xffff0000, v174
	v_lshlrev_b32_e32 v4, 16, v175
	v_and_b32_e32 v5, 0xffff0000, v175
	v_pk_add_f32 v[98:99], v[98:99], v[2:3]
	v_pk_add_f32 v[100:101], v[100:101], v[4:5]
	v_lshlrev_b32_e32 v2, 16, v172
	v_and_b32_e32 v3, 0xffff0000, v172
	v_lshlrev_b32_e32 v4, 16, v173
	v_and_b32_e32 v5, 0xffff0000, v173
	v_pk_add_f32 v[90:91], v[90:91], v[2:3]
	v_pk_add_f32 v[92:93], v[92:93], v[4:5]
	v_lshlrev_b32_e32 v2, 16, v176
	v_and_b32_e32 v3, 0xffff0000, v176
	v_lshlrev_b32_e32 v4, 16, v177
	v_and_b32_e32 v5, 0xffff0000, v177
	v_pk_add_f32 v[90:91], v[90:91], v[2:3]
	v_pk_add_f32 v[92:93], v[92:93], v[4:5]
	v_cvt_pk_bf16_f32 v2, v98, v99
	v_cvt_pk_bf16_f32 v3, v100, v101
	v_cvt_pk_bf16_f32 v4, v90, v91
	v_cvt_pk_bf16_f32 v5, v92, v93
	v_add_u32_e32 v130, 0x10000, v131
	global_store_dwordx4 v130, v[2:5], s[26:27]
	s_nop 1
	s_mov_b32 s0, 0x1a000
	buffer_load_dwordx4 v[170:173], v132, s[36:39], s0 offen
	s_mov_b32 s0, 0x3a000
	buffer_load_dwordx4 v[174:177], v132, s[36:39], s0 offen
	s_waitcnt vmcnt(17)
	v_lshlrev_b32_e32 v2, 16, v178
	v_and_b32_e32 v3, 0xffff0000, v178
	v_lshlrev_b32_e32 v4, 16, v179
	v_and_b32_e32 v5, 0xffff0000, v179
	v_pk_add_f32 v[86:87], v[86:87], v[2:3]
	v_pk_add_f32 v[88:89], v[88:89], v[4:5]
	v_lshlrev_b32_e32 v2, 16, v182
	v_and_b32_e32 v3, 0xffff0000, v182
	v_lshlrev_b32_e32 v4, 16, v183
	v_and_b32_e32 v5, 0xffff0000, v183
	v_pk_add_f32 v[86:87], v[86:87], v[2:3]
	v_pk_add_f32 v[88:89], v[88:89], v[4:5]
	v_lshlrev_b32_e32 v2, 16, v180
	v_and_b32_e32 v3, 0xffff0000, v180
	v_lshlrev_b32_e32 v4, 16, v181
	v_and_b32_e32 v5, 0xffff0000, v181
	v_pk_add_f32 v[78:79], v[78:79], v[2:3]
	v_pk_add_f32 v[80:81], v[80:81], v[4:5]
	v_lshlrev_b32_e32 v2, 16, v184
	v_and_b32_e32 v3, 0xffff0000, v184
	v_lshlrev_b32_e32 v4, 16, v185
	v_and_b32_e32 v5, 0xffff0000, v185
	v_pk_add_f32 v[78:79], v[78:79], v[2:3]
	v_pk_add_f32 v[80:81], v[80:81], v[4:5]
	v_cvt_pk_bf16_f32 v2, v86, v87
	v_cvt_pk_bf16_f32 v3, v88, v89
	v_cvt_pk_bf16_f32 v4, v78, v79
	v_cvt_pk_bf16_f32 v5, v80, v81
	v_add_u32_e32 v130, 0x10000, v131
	global_store_dwordx4 v130, v[2:5], s[26:27] offset:256
	s_nop 1
	s_mov_b32 s0, 0x14000
	buffer_load_dwordx4 v[178:181], v132, s[36:39], s0 offen
	s_mov_b32 s0, 0x34000
	buffer_load_dwordx4 v[182:185], v132, s[36:39], s0 offen
	s_waitcnt vmcnt(18)
	v_lshlrev_b32_e32 v2, 16, v186
	v_and_b32_e32 v3, 0xffff0000, v186
	v_lshlrev_b32_e32 v4, 16, v187
	v_and_b32_e32 v5, 0xffff0000, v187
	v_pk_add_f32 v[82:83], v[82:83], v[2:3]
	v_pk_add_f32 v[84:85], v[84:85], v[4:5]
	v_lshlrev_b32_e32 v2, 16, v190
	v_and_b32_e32 v3, 0xffff0000, v190
	v_lshlrev_b32_e32 v4, 16, v191
	v_and_b32_e32 v5, 0xffff0000, v191
	v_pk_add_f32 v[82:83], v[82:83], v[2:3]
	v_pk_add_f32 v[84:85], v[84:85], v[4:5]
	v_lshlrev_b32_e32 v2, 16, v188
	v_and_b32_e32 v3, 0xffff0000, v188
	v_lshlrev_b32_e32 v4, 16, v189
	v_and_b32_e32 v5, 0xffff0000, v189
	v_pk_add_f32 v[74:75], v[74:75], v[2:3]
	v_pk_add_f32 v[76:77], v[76:77], v[4:5]
	v_lshlrev_b32_e32 v2, 16, v192
	v_and_b32_e32 v3, 0xffff0000, v192
	v_lshlrev_b32_e32 v4, 16, v193
	v_and_b32_e32 v5, 0xffff0000, v193
	v_pk_add_f32 v[74:75], v[74:75], v[2:3]
	v_pk_add_f32 v[76:77], v[76:77], v[4:5]
	v_cvt_pk_bf16_f32 v2, v82, v83
	v_cvt_pk_bf16_f32 v3, v84, v85
	v_cvt_pk_bf16_f32 v4, v74, v75
	v_cvt_pk_bf16_f32 v5, v76, v77
	v_add_u32_e32 v130, 0x18000, v131
	global_store_dwordx4 v130, v[2:5], s[26:27]
	s_nop 1
	s_mov_b32 s0, 0x1c000
	buffer_load_dwordx4 v[186:189], v132, s[36:39], s0 offen
	s_mov_b32 s0, 0x3c000
	buffer_load_dwordx4 v[190:193], v132, s[36:39], s0 offen
	s_waitcnt vmcnt(18)
	v_lshlrev_b32_e32 v2, 16, v138
	v_and_b32_e32 v3, 0xffff0000, v138
	v_lshlrev_b32_e32 v4, 16, v139
	v_and_b32_e32 v5, 0xffff0000, v139
	v_pk_add_f32 v[70:71], v[70:71], v[2:3]
	v_pk_add_f32 v[72:73], v[72:73], v[4:5]
	v_lshlrev_b32_e32 v2, 16, v142
	v_and_b32_e32 v3, 0xffff0000, v142
	v_lshlrev_b32_e32 v4, 16, v143
	v_and_b32_e32 v5, 0xffff0000, v143
	v_pk_add_f32 v[70:71], v[70:71], v[2:3]
	v_pk_add_f32 v[72:73], v[72:73], v[4:5]
	v_lshlrev_b32_e32 v2, 16, v140
	v_and_b32_e32 v3, 0xffff0000, v140
	v_lshlrev_b32_e32 v4, 16, v141
	v_and_b32_e32 v5, 0xffff0000, v141
	v_pk_add_f32 v[66:67], v[66:67], v[2:3]
	v_pk_add_f32 v[68:69], v[68:69], v[4:5]
	v_lshlrev_b32_e32 v2, 16, v144
	v_and_b32_e32 v3, 0xffff0000, v144
	v_lshlrev_b32_e32 v4, 16, v145
	v_and_b32_e32 v5, 0xffff0000, v145
	v_pk_add_f32 v[66:67], v[66:67], v[2:3]
	v_pk_add_f32 v[68:69], v[68:69], v[4:5]
	v_cvt_pk_bf16_f32 v2, v70, v71
	v_cvt_pk_bf16_f32 v3, v72, v73
	v_cvt_pk_bf16_f32 v4, v66, v67
	v_cvt_pk_bf16_f32 v5, v68, v69
	v_add_u32_e32 v130, 0x18000, v131
	global_store_dwordx4 v130, v[2:5], s[26:27] offset:256
	s_nop 1
	s_mov_b32 s0, 0x16000
	buffer_load_dwordx4 v[138:141], v132, s[36:39], s0 offen
	s_mov_b32 s0, 0x36000
	buffer_load_dwordx4 v[142:145], v132, s[36:39], s0 offen
	s_waitcnt vmcnt(18)
	v_lshlrev_b32_e32 v2, 16, v146
	v_and_b32_e32 v3, 0xffff0000, v146
	v_lshlrev_b32_e32 v4, 16, v147
	v_and_b32_e32 v5, 0xffff0000, v147
	v_pk_add_f32 v[62:63], v[62:63], v[2:3]
	v_pk_add_f32 v[64:65], v[64:65], v[4:5]
	v_lshlrev_b32_e32 v2, 16, v150
	v_and_b32_e32 v3, 0xffff0000, v150
	v_lshlrev_b32_e32 v4, 16, v151
	v_and_b32_e32 v5, 0xffff0000, v151
	v_pk_add_f32 v[62:63], v[62:63], v[2:3]
	v_pk_add_f32 v[64:65], v[64:65], v[4:5]
	v_lshlrev_b32_e32 v2, 16, v148
	v_and_b32_e32 v3, 0xffff0000, v148
	v_lshlrev_b32_e32 v4, 16, v149
	v_and_b32_e32 v5, 0xffff0000, v149
	v_pk_add_f32 v[58:59], v[58:59], v[2:3]
	v_pk_add_f32 v[60:61], v[60:61], v[4:5]
	v_lshlrev_b32_e32 v2, 16, v152
	v_and_b32_e32 v3, 0xffff0000, v152
	v_lshlrev_b32_e32 v4, 16, v153
	v_and_b32_e32 v5, 0xffff0000, v153
	v_pk_add_f32 v[58:59], v[58:59], v[2:3]
	v_pk_add_f32 v[60:61], v[60:61], v[4:5]
	v_cvt_pk_bf16_f32 v2, v62, v63
	v_cvt_pk_bf16_f32 v3, v64, v65
	v_cvt_pk_bf16_f32 v4, v58, v59
	v_cvt_pk_bf16_f32 v5, v60, v61
	v_add_u32_e32 v130, 0x40000, v131
	global_store_dwordx4 v130, v[2:5], s[26:27]
	s_nop 1
	s_mov_b32 s0, 0x1e000
	buffer_load_dwordx4 v[146:149], v132, s[36:39], s0 offen
	s_mov_b32 s0, 0x3e000
	buffer_load_dwordx4 v[150:153], v132, s[36:39], s0 offen
	s_waitcnt vmcnt(18)
	v_lshlrev_b32_e32 v2, 16, v154
	v_and_b32_e32 v3, 0xffff0000, v154
	v_lshlrev_b32_e32 v4, 16, v155
	v_and_b32_e32 v5, 0xffff0000, v155
	v_pk_add_f32 v[54:55], v[54:55], v[2:3]
	v_pk_add_f32 v[56:57], v[56:57], v[4:5]
	v_lshlrev_b32_e32 v2, 16, v158
	v_and_b32_e32 v3, 0xffff0000, v158
	v_lshlrev_b32_e32 v4, 16, v159
	v_and_b32_e32 v5, 0xffff0000, v159
	v_pk_add_f32 v[54:55], v[54:55], v[2:3]
	v_pk_add_f32 v[56:57], v[56:57], v[4:5]
	v_lshlrev_b32_e32 v2, 16, v156
	v_and_b32_e32 v3, 0xffff0000, v156
	v_lshlrev_b32_e32 v4, 16, v157
	v_and_b32_e32 v5, 0xffff0000, v157
	v_pk_add_f32 v[46:47], v[46:47], v[2:3]
	v_pk_add_f32 v[48:49], v[48:49], v[4:5]
	v_lshlrev_b32_e32 v2, 16, v160
	v_and_b32_e32 v3, 0xffff0000, v160
	v_lshlrev_b32_e32 v4, 16, v161
	v_and_b32_e32 v5, 0xffff0000, v161
	v_pk_add_f32 v[46:47], v[46:47], v[2:3]
	v_pk_add_f32 v[48:49], v[48:49], v[4:5]
	v_cvt_pk_bf16_f32 v2, v54, v55
	v_cvt_pk_bf16_f32 v3, v56, v57
	v_cvt_pk_bf16_f32 v4, v46, v47
	v_cvt_pk_bf16_f32 v5, v48, v49
	v_add_u32_e32 v130, 0x40000, v131
	global_store_dwordx4 v130, v[2:5], s[26:27] offset:256
	s_nop 1
	s_waitcnt vmcnt(16)
	v_lshlrev_b32_e32 v2, 16, v162
	v_and_b32_e32 v3, 0xffff0000, v162
	v_lshlrev_b32_e32 v4, 16, v163
	v_and_b32_e32 v5, 0xffff0000, v163
	v_pk_add_f32 v[50:51], v[50:51], v[2:3]
	v_pk_add_f32 v[52:53], v[52:53], v[4:5]
	v_lshlrev_b32_e32 v2, 16, v166
	v_and_b32_e32 v3, 0xffff0000, v166
	v_lshlrev_b32_e32 v4, 16, v167
	v_and_b32_e32 v5, 0xffff0000, v167
	v_pk_add_f32 v[50:51], v[50:51], v[2:3]
	v_pk_add_f32 v[52:53], v[52:53], v[4:5]
	v_lshlrev_b32_e32 v2, 16, v164
	v_and_b32_e32 v3, 0xffff0000, v164
	v_lshlrev_b32_e32 v4, 16, v165
	v_and_b32_e32 v5, 0xffff0000, v165
	v_pk_add_f32 v[42:43], v[42:43], v[2:3]
	v_pk_add_f32 v[44:45], v[44:45], v[4:5]
	v_lshlrev_b32_e32 v2, 16, v168
	v_and_b32_e32 v3, 0xffff0000, v168
	v_lshlrev_b32_e32 v4, 16, v169
	v_and_b32_e32 v5, 0xffff0000, v169
	v_pk_add_f32 v[42:43], v[42:43], v[2:3]
	v_pk_add_f32 v[44:45], v[44:45], v[4:5]
	v_cvt_pk_bf16_f32 v2, v50, v51
	v_cvt_pk_bf16_f32 v3, v52, v53
	v_cvt_pk_bf16_f32 v4, v42, v43
	v_cvt_pk_bf16_f32 v5, v44, v45
	v_add_u32_e32 v130, 0x48000, v131
	global_store_dwordx4 v130, v[2:5], s[26:27]
	s_nop 1
	s_waitcnt vmcnt(14)
	v_lshlrev_b32_e32 v2, 16, v170
	v_and_b32_e32 v3, 0xffff0000, v170
	v_lshlrev_b32_e32 v4, 16, v171
	v_and_b32_e32 v5, 0xffff0000, v171
	v_pk_add_f32 v[38:39], v[38:39], v[2:3]
	v_pk_add_f32 v[40:41], v[40:41], v[4:5]
	v_lshlrev_b32_e32 v2, 16, v174
	v_and_b32_e32 v3, 0xffff0000, v174
	v_lshlrev_b32_e32 v4, 16, v175
	v_and_b32_e32 v5, 0xffff0000, v175
	v_pk_add_f32 v[38:39], v[38:39], v[2:3]
	v_pk_add_f32 v[40:41], v[40:41], v[4:5]
	v_lshlrev_b32_e32 v2, 16, v172
	v_and_b32_e32 v3, 0xffff0000, v172
	v_lshlrev_b32_e32 v4, 16, v173
	v_and_b32_e32 v5, 0xffff0000, v173
	v_pk_add_f32 v[30:31], v[30:31], v[2:3]
	v_pk_add_f32 v[32:33], v[32:33], v[4:5]
	v_lshlrev_b32_e32 v2, 16, v176
	v_and_b32_e32 v3, 0xffff0000, v176
	v_lshlrev_b32_e32 v4, 16, v177
	v_and_b32_e32 v5, 0xffff0000, v177
	v_pk_add_f32 v[30:31], v[30:31], v[2:3]
	v_pk_add_f32 v[32:33], v[32:33], v[4:5]
	v_cvt_pk_bf16_f32 v2, v38, v39
	v_cvt_pk_bf16_f32 v3, v40, v41
	v_cvt_pk_bf16_f32 v4, v30, v31
	v_cvt_pk_bf16_f32 v5, v32, v33
	v_add_u32_e32 v130, 0x48000, v131
	global_store_dwordx4 v130, v[2:5], s[26:27] offset:256
	s_nop 1
	s_waitcnt vmcnt(12)
	v_lshlrev_b32_e32 v2, 16, v178
	v_and_b32_e32 v3, 0xffff0000, v178
	v_lshlrev_b32_e32 v4, 16, v179
	v_and_b32_e32 v5, 0xffff0000, v179
	v_pk_add_f32 v[34:35], v[34:35], v[2:3]
	v_pk_add_f32 v[36:37], v[36:37], v[4:5]
	v_lshlrev_b32_e32 v2, 16, v182
	v_and_b32_e32 v3, 0xffff0000, v182
	v_lshlrev_b32_e32 v4, 16, v183
	v_and_b32_e32 v5, 0xffff0000, v183
	v_pk_add_f32 v[34:35], v[34:35], v[2:3]
	v_pk_add_f32 v[36:37], v[36:37], v[4:5]
	v_lshlrev_b32_e32 v2, 16, v180
	v_and_b32_e32 v3, 0xffff0000, v180
	v_lshlrev_b32_e32 v4, 16, v181
	v_and_b32_e32 v5, 0xffff0000, v181
	v_pk_add_f32 v[26:27], v[26:27], v[2:3]
	v_pk_add_f32 v[28:29], v[28:29], v[4:5]
	v_lshlrev_b32_e32 v2, 16, v184
	v_and_b32_e32 v3, 0xffff0000, v184
	v_lshlrev_b32_e32 v4, 16, v185
	v_and_b32_e32 v5, 0xffff0000, v185
	v_pk_add_f32 v[26:27], v[26:27], v[2:3]
	v_pk_add_f32 v[28:29], v[28:29], v[4:5]
	v_cvt_pk_bf16_f32 v2, v34, v35
	v_cvt_pk_bf16_f32 v3, v36, v37
	v_cvt_pk_bf16_f32 v4, v26, v27
	v_cvt_pk_bf16_f32 v5, v28, v29
	v_add_u32_e32 v130, 0x50000, v131
	global_store_dwordx4 v130, v[2:5], s[26:27]
	s_nop 1
	s_waitcnt vmcnt(10)
	v_lshlrev_b32_e32 v2, 16, v186
	v_and_b32_e32 v3, 0xffff0000, v186
	v_lshlrev_b32_e32 v4, 16, v187
	v_and_b32_e32 v5, 0xffff0000, v187
	v_pk_add_f32 v[22:23], v[22:23], v[2:3]
	v_pk_add_f32 v[24:25], v[24:25], v[4:5]
	v_lshlrev_b32_e32 v2, 16, v190
	v_and_b32_e32 v3, 0xffff0000, v190
	v_lshlrev_b32_e32 v4, 16, v191
	v_and_b32_e32 v5, 0xffff0000, v191
	v_pk_add_f32 v[22:23], v[22:23], v[2:3]
	v_pk_add_f32 v[24:25], v[24:25], v[4:5]
	v_lshlrev_b32_e32 v2, 16, v188
	v_and_b32_e32 v3, 0xffff0000, v188
	v_lshlrev_b32_e32 v4, 16, v189
	v_and_b32_e32 v5, 0xffff0000, v189
	v_pk_add_f32 v[14:15], v[14:15], v[2:3]
	v_pk_add_f32 v[16:17], v[16:17], v[4:5]
	v_lshlrev_b32_e32 v2, 16, v192
	v_and_b32_e32 v3, 0xffff0000, v192
	v_lshlrev_b32_e32 v4, 16, v193
	v_and_b32_e32 v5, 0xffff0000, v193
	v_pk_add_f32 v[14:15], v[14:15], v[2:3]
	v_pk_add_f32 v[16:17], v[16:17], v[4:5]
	v_cvt_pk_bf16_f32 v2, v22, v23
	v_cvt_pk_bf16_f32 v3, v24, v25
	v_cvt_pk_bf16_f32 v4, v14, v15
	v_cvt_pk_bf16_f32 v5, v16, v17
	v_add_u32_e32 v130, 0x50000, v131
	global_store_dwordx4 v130, v[2:5], s[26:27] offset:256
	s_nop 1
	s_waitcnt vmcnt(8)
	v_lshlrev_b32_e32 v2, 16, v138
	v_and_b32_e32 v3, 0xffff0000, v138
	v_lshlrev_b32_e32 v4, 16, v139
	v_and_b32_e32 v5, 0xffff0000, v139
	v_pk_add_f32 v[18:19], v[18:19], v[2:3]
	v_pk_add_f32 v[20:21], v[20:21], v[4:5]
	v_lshlrev_b32_e32 v2, 16, v142
	v_and_b32_e32 v3, 0xffff0000, v142
	v_lshlrev_b32_e32 v4, 16, v143
	v_and_b32_e32 v5, 0xffff0000, v143
	v_pk_add_f32 v[18:19], v[18:19], v[2:3]
	v_pk_add_f32 v[20:21], v[20:21], v[4:5]
	v_lshlrev_b32_e32 v2, 16, v140
	v_and_b32_e32 v3, 0xffff0000, v140
	v_lshlrev_b32_e32 v4, 16, v141
	v_and_b32_e32 v5, 0xffff0000, v141
	v_pk_add_f32 v[136:137], v[136:137], v[2:3]
	v_pk_add_f32 v[134:135], v[134:135], v[4:5]
	v_lshlrev_b32_e32 v2, 16, v144
	v_and_b32_e32 v3, 0xffff0000, v144
	v_lshlrev_b32_e32 v4, 16, v145
	v_and_b32_e32 v5, 0xffff0000, v145
	v_pk_add_f32 v[136:137], v[136:137], v[2:3]
	v_pk_add_f32 v[134:135], v[134:135], v[4:5]
	v_cvt_pk_bf16_f32 v2, v18, v19
	v_cvt_pk_bf16_f32 v3, v20, v21
	v_cvt_pk_bf16_f32 v4, v136, v137
	v_cvt_pk_bf16_f32 v5, v134, v135
	v_add_u32_e32 v130, 0x58000, v131
	global_store_dwordx4 v130, v[2:5], s[26:27]
	s_nop 1
	s_waitcnt vmcnt(6)
	v_lshlrev_b32_e32 v2, 16, v146
	v_and_b32_e32 v3, 0xffff0000, v146
	v_lshlrev_b32_e32 v4, 16, v147
	v_and_b32_e32 v5, 0xffff0000, v147
	v_pk_add_f32 v[6:7], v[6:7], v[2:3]
	v_pk_add_f32 v[8:9], v[8:9], v[4:5]
	v_lshlrev_b32_e32 v2, 16, v150
	v_and_b32_e32 v3, 0xffff0000, v150
	v_lshlrev_b32_e32 v4, 16, v151
	v_and_b32_e32 v5, 0xffff0000, v151
	v_pk_add_f32 v[6:7], v[6:7], v[2:3]
	v_pk_add_f32 v[8:9], v[8:9], v[4:5]
	v_lshlrev_b32_e32 v2, 16, v148
	v_and_b32_e32 v3, 0xffff0000, v148
	v_lshlrev_b32_e32 v4, 16, v149
	v_and_b32_e32 v5, 0xffff0000, v149
	v_pk_add_f32 v[12:13], v[12:13], v[2:3]
	v_pk_add_f32 v[10:11], v[10:11], v[4:5]
	v_lshlrev_b32_e32 v2, 16, v152
	v_and_b32_e32 v3, 0xffff0000, v152
	v_lshlrev_b32_e32 v4, 16, v153
	v_and_b32_e32 v5, 0xffff0000, v153
	v_pk_add_f32 v[12:13], v[12:13], v[2:3]
	v_pk_add_f32 v[10:11], v[10:11], v[4:5]
	v_cvt_pk_bf16_f32 v2, v6, v7
	v_cvt_pk_bf16_f32 v3, v8, v9
	v_cvt_pk_bf16_f32 v4, v12, v13
	v_cvt_pk_bf16_f32 v5, v10, v11
	v_add_u32_e32 v130, 0x58000, v131
	global_store_dwordx4 v130, v[2:5], s[26:27] offset:256
	s_nop 1
	s_mov_b32 s26, s38
	v_writelane_b32 v254, s24, 28
	v_writelane_b32 v254, s25, 29
	v_writelane_b32 v254, s26, 30
	v_writelane_b32 v254, s27, 31
